# v35 + NSA top-k bit search run under EXEC = candidate mask (one s_and_b64 less per step, exact)
# speedup vs baseline: 1.0710x; 1.0702x over previous
; __device__ __forceinline__ void nsa_item(const Params& P, int b, int g, int c, const bf16_t* z, const bf16_t* kcv, bf16_t* y, char* lds) {
;     ...
;       u64 mk = V;
;       if (c + 1 > 16) {
;         unsigned thr = 0u;
;     ...
;         const u64 G = __ballot(u > thr) & V, E = __ballot(u == thr) & V;
;         const int need = 16 - (int)__popcll(G);
;         const int below = (int)__popcll(E & ((1ull << lane) - 1ull));
;         const bool se = (((E >> lane) & 1ull) != 0ull) && (below < need);
;         mk = G | __ballot(se);
.LBB0_338:
	s_andn2_b64 vcc, exec, s[34:35]
	s_mov_b64 s[0:1], s[30:31]
	s_cbranch_vccnz .LBB0_340
	v_add_u32_e32 v22, 0xffffbf00, v21
	ds_read_b32 v22, v22
	ds_read_b32 v23, v21
	s_brev_b32 s46, -4
	s_waitcnt lgkmcnt(0)
	v_add_f32_e32 v22, v22, v23
	v_cndmask_b32_e64 v22, v22, v226, s[38:39]
	s_and_saveexec_b64 s[0:1], s[30:31]
	v_cmp_lt_u32_e32 vcc, s46, v22
	s_bcnt1_i32_b64 s46, vcc
	s_cmp_gt_u32 s46, 15
	s_cselect_b32 s16, 2.0, 0
	s_or_b32 s17, s16, 0x20000000
	v_cmp_le_u32_e32 vcc, s17, v22
	s_bcnt1_i32_b64 s46, vcc
	s_cmp_gt_u32 s46, 15
	s_cselect_b32 s16, s17, s16
	s_or_b32 s17, s16, 0x10000000
	v_cmp_le_u32_e32 vcc, s17, v22
	s_bcnt1_i32_b64 s46, vcc
	s_cmp_gt_u32 s46, 15
	s_cselect_b32 s16, s17, s16
	s_or_b32 s17, s16, 0x8000000
	v_cmp_le_u32_e32 vcc, s17, v22
	s_bcnt1_i32_b64 s46, vcc
	s_cmp_gt_u32 s46, 15
	s_cselect_b32 s16, s17, s16
	s_or_b32 s17, s16, 0x4000000
	v_cmp_le_u32_e32 vcc, s17, v22
	s_bcnt1_i32_b64 s46, vcc
	s_cmp_gt_u32 s46, 15
	s_cselect_b32 s16, s17, s16
	s_or_b32 s17, s16, 0x2000000
	v_cmp_le_u32_e32 vcc, s17, v22
	s_bcnt1_i32_b64 s46, vcc
	s_cmp_gt_u32 s46, 15
	s_cselect_b32 s16, s17, s16
	s_or_b32 s17, s16, 0x1000000
	v_cmp_le_u32_e32 vcc, s17, v22
	s_bcnt1_i32_b64 s46, vcc
	s_cmp_gt_u32 s46, 15
	s_cselect_b32 s16, s17, s16
	s_or_b32 s17, s16, 0x800000
	v_cmp_le_u32_e32 vcc, s17, v22
	s_bcnt1_i32_b64 s46, vcc
	s_cmp_gt_u32 s46, 15
	s_cselect_b32 s16, s17, s16
	s_or_b32 s17, s16, 0x400000
	v_cmp_le_u32_e32 vcc, s17, v22
	s_bcnt1_i32_b64 s46, vcc
	s_cmp_gt_u32 s46, 15
	s_cselect_b32 s16, s17, s16
	s_or_b32 s17, s16, 0x200000
	v_cmp_le_u32_e32 vcc, s17, v22
	s_bcnt1_i32_b64 s46, vcc
	s_cmp_gt_u32 s46, 15
	s_cselect_b32 s16, s17, s16
	s_or_b32 s17, s16, 0x100000
	v_cmp_le_u32_e32 vcc, s17, v22
	s_bcnt1_i32_b64 s46, vcc
	s_cmp_gt_u32 s46, 15
	s_cselect_b32 s16, s17, s16
	s_or_b32 s17, s16, 0x80000
	v_cmp_le_u32_e32 vcc, s17, v22
	s_bcnt1_i32_b64 s46, vcc
	s_cmp_gt_u32 s46, 15
	s_cselect_b32 s16, s17, s16
	s_or_b32 s17, s16, 0x40000
	v_cmp_le_u32_e32 vcc, s17, v22
	s_bcnt1_i32_b64 s46, vcc
	s_cmp_gt_u32 s46, 15
	s_cselect_b32 s16, s17, s16
	s_or_b32 s17, s16, 0x20000
	v_cmp_le_u32_e32 vcc, s17, v22
	s_bcnt1_i32_b64 s46, vcc
	s_cmp_gt_u32 s46, 15
	s_cselect_b32 s16, s17, s16
	s_or_b32 s17, s16, 0x10000
	v_cmp_le_u32_e32 vcc, s17, v22
	s_bcnt1_i32_b64 s46, vcc
	s_cmp_gt_u32 s46, 15
	s_cselect_b32 s16, s17, s16
	s_or_b32 s17, s16, 0x8000
	v_cmp_le_u32_e32 vcc, s17, v22
	s_bcnt1_i32_b64 s46, vcc
	s_cmp_gt_u32 s46, 15
	s_cselect_b32 s16, s17, s16
	s_or_b32 s17, s16, 0x4000
	v_cmp_le_u32_e32 vcc, s17, v22
	s_bcnt1_i32_b64 s46, vcc
	s_cmp_gt_u32 s46, 15
	s_cselect_b32 s16, s17, s16
	s_or_b32 s17, s16, 0x2000
	v_cmp_le_u32_e32 vcc, s17, v22
	s_bcnt1_i32_b64 s46, vcc
	s_cmp_gt_u32 s46, 15
	s_cselect_b32 s16, s17, s16
	s_or_b32 s17, s16, 0x1000
	v_cmp_le_u32_e32 vcc, s17, v22
	s_bcnt1_i32_b64 s46, vcc
	s_cmp_gt_u32 s46, 15
	s_cselect_b32 s16, s17, s16
	s_or_b32 s17, s16, 0x800
	v_cmp_le_u32_e32 vcc, s17, v22
	s_bcnt1_i32_b64 s46, vcc
	s_cmp_gt_u32 s46, 15
	s_cselect_b32 s16, s17, s16
	s_or_b32 s17, s16, 0x400
	v_cmp_le_u32_e32 vcc, s17, v22
	s_bcnt1_i32_b64 s46, vcc
	s_cmp_gt_u32 s46, 15
	s_cselect_b32 s16, s17, s16
	s_or_b32 s17, s16, 0x200
	v_cmp_le_u32_e32 vcc, s17, v22
	s_bcnt1_i32_b64 s46, vcc
	s_cmp_gt_u32 s46, 15
	s_cselect_b32 s16, s17, s16
	s_or_b32 s17, s16, 0x100
	v_cmp_le_u32_e32 vcc, s17, v22
	s_bcnt1_i32_b64 s46, vcc
	s_cmp_gt_u32 s46, 15
	s_cselect_b32 s16, s17, s16
	s_or_b32 s17, s16, 0x80
	v_cmp_le_u32_e32 vcc, s17, v22
	s_bcnt1_i32_b64 s46, vcc
	s_cmp_gt_u32 s46, 15
	s_cselect_b32 s16, s17, s16
	s_or_b32 s17, s16, 64
	v_cmp_le_u32_e32 vcc, s17, v22
	s_bcnt1_i32_b64 s46, vcc
	s_cmp_gt_u32 s46, 15
	s_cselect_b32 s16, s17, s16
	s_or_b32 s17, s16, 32
	v_cmp_le_u32_e32 vcc, s17, v22
	s_bcnt1_i32_b64 s46, vcc
	s_cmp_gt_u32 s46, 15
	s_cselect_b32 s16, s17, s16
	s_or_b32 s17, s16, 16
	v_cmp_le_u32_e32 vcc, s17, v22
	s_bcnt1_i32_b64 s46, vcc
	s_cmp_gt_u32 s46, 15
	s_cselect_b32 s16, s17, s16
	s_or_b32 s17, s16, 8
	v_cmp_le_u32_e32 vcc, s17, v22
	s_bcnt1_i32_b64 s46, vcc
	s_cmp_gt_u32 s46, 15
	s_cselect_b32 s16, s17, s16
	s_or_b32 s17, s16, 4
	v_cmp_le_u32_e32 vcc, s17, v22
	s_bcnt1_i32_b64 s46, vcc
	s_cmp_gt_u32 s46, 15
	s_cselect_b32 s16, s17, s16
	s_or_b32 s17, s16, 2
	v_cmp_le_u32_e32 vcc, s17, v22
	s_bcnt1_i32_b64 s46, vcc
	s_cmp_gt_u32 s46, 15
	s_cselect_b32 s16, s17, s16
	s_or_b32 s17, s16, 1
	v_cmp_le_u32_e32 vcc, s17, v22
	s_bcnt1_i32_b64 s46, vcc
	s_mov_b64 exec, s[0:1]
	v_cmp_gt_u64_e64 s[0:1], s[46:47], 15
	s_and_b64 s[0:1], s[0:1], exec
	s_cselect_b32 s0, s17, s16
	v_cmp_lt_u32_e32 vcc, s0, v22
	v_cmp_eq_u32_e64 s[0:1], s0, v22
	s_and_b64 s[0:1], s[0:1], s[30:31]
	s_and_b64 s[16:17], vcc, s[30:31]
	v_and_b32_e32 v22, s0, v16
	s_bcnt1_i32_b64 s46, s[16:17]
	v_and_b32_e32 v23, s1, v17
	v_bcnt_u32_b32 v22, v22, 0
	s_sub_i32 s46, 16, s46
	v_bcnt_u32_b32 v24, v23, v22
	v_and_b32_e32 v23, s1, v19
	v_and_b32_e32 v22, s0, v18
	v_cmp_ne_u64_e32 vcc, 0, v[22:23]
	v_cmp_gt_i32_e64 s[0:1], s46, v24
	s_and_b64 s[0:1], vcc, s[0:1]
	s_nop 0
	v_cndmask_b32_e64 v22, 0, 1, s[0:1]
	v_cmp_ne_u32_e32 vcc, 0, v22
	s_or_b64 s[0:1], vcc, s[16:17]
